# P2 tile order: xp column tiles last per XCD (cache-resident for P3 pooling) + P3 pool/sample rebalance
# speedup vs baseline: 1.0308x; 1.0209x over previous
;     __device__ bool next(int i, Unit& u) const { if (i >= 2) return false; const int x = c & 7, j = c >> 3; u.pm = 64 * i + 8 * x + (j >> 2); u.pn = j & 3; u.ao = 0; u.bo = 0; u.ks = 0; return true; }
;     __device__ bool next(int i, Unit& u) const { if (i >= 1 || c >= 64) return false; u.pm = 128 + (c & 3); u.pn = (c >> 2) & 3; u.ks = c >> 4; u.ao = u.ks * 512; u.bo = u.ks * 512; return true; }
;     __device__ bool next(int i, Unit& u) const {
;         const long L = (long)i * G + c; if (L >= nwg) return false;
;         int wgid = (int)L; { const int q = nwg / NXCD, r = nwg % NXCD, xcd = wgid % NXCD, off = wgid / NXCD; wgid = (xcd < r ? xcd * (q + 1) : r * (q + 1) + (xcd - r) * q) + off; }
;         const int nig = WGM * nN, gid = wgid / nig, fm = gid * WGM, gsz = (nM - fm) < WGM ? (nM - fm) : WGM;
;         u.pm = fm + ((wgid % nig) % gsz); u.pn = (wgid % nig) / gsz; u.ao = u.pn * acol; u.bo = 0; u.ks = 0; return true;
;     }
.LBB0_175:
	s_or_b64 exec, exec, s[0:1]
	s_waitcnt vmcnt(1)
	v_mov_b32_e32 v8, v180
	s_cmpk_lt_i32 s2, 0xe70
	s_waitcnt lgkmcnt(0)
	s_barrier
	s_cselect_b64 s[0:1], -1, 0
	s_cmpk_gt_i32 s2, 0xe6f
	v_readfirstlane_b32 s12, v8
	s_cbranch_scc1 .LBB0_177
	s_and_b32 s4, s2, 7
	s_lshr_b32 s5, s2, 3
	s_cmpk_lt_u32 s5, 0x18c
	s_cbranch_scc0 .Lxpl1_xp
	s_mul_i32 s4, s4, 0x18c
	s_add_i32 s4, s4, s5
	s_lshr_b32 s6, s4, 6
	s_mul_i32 s6, s6, 0xaaab
	s_lshr_b32 s6, s6, 17
	s_mul_i32 s7, s6, 0xc0
	s_sub_i32 s8, s4, s7
	s_mov_b32 s10, 4
	s_branch .Lxpl1_common
.Lxpl1_xp:
	s_mul_i32 s4, s4, 66
	s_add_i32 s4, s4, s5
	s_sub_i32 s4, s4, 0x18c
	s_lshr_b32 s6, s4, 5
	s_and_b32 s8, s4, 31
	s_mov_b32 s10, 0
.Lxpl1_common:
	s_lshl_b32 s6, s6, 3
	s_cmp_eq_u32 s6, 0x80
	s_cselect_b32 s7, 3, 7
	s_cselect_b32 s9, 2, 3
	s_and_b32 s4, s8, s7
	s_add_i32 s4, s4, s6
	s_lshr_b32 s8, s8, s9
	s_add_i32 s10, s10, s8

;     __device__ bool next(int i, Unit& u) const { if (i >= 2) return false; const int x = c & 7, j = c >> 3; u.pm = 64 * i + 8 * x + (j >> 2); u.pn = j & 3; u.ao = 0; u.bo = 0; u.ks = 0; return true; }
;     __device__ bool next(int i, Unit& u) const { if (i >= 1 || c >= 64) return false; u.pm = 128 + (c & 3); u.pn = (c >> 2) & 3; u.ks = c >> 4; u.ao = u.ks * 512; u.bo = u.ks * 512; return true; }
;     __device__ bool next(int i, Unit& u) const {
;         const long L = (long)i * G + c; if (L >= nwg) return false;
;         int wgid = (int)L; { const int q = nwg / NXCD, r = nwg % NXCD, xcd = wgid % NXCD, off = wgid / NXCD; wgid = (xcd < r ? xcd * (q + 1) : r * (q + 1) + (xcd - r) * q) + off; }
;         const int nig = WGM * nN, gid = wgid / nig, fm = gid * WGM, gsz = (nM - fm) < WGM ? (nM - fm) : WGM;
;         u.pm = fm + ((wgid % nig) % gsz); u.pn = (wgid % nig) / gsz; u.ao = u.pn * acol; u.bo = 0; u.ks = 0; return true;
;     }
; template <class Epi, class Sched, bool ALIGN_EPI, bool SP2>
; __device__ __forceinline__ void gemm_phase(LAS unsigned char* lds, const Gemm g, const Sched& S, const Epi& E) {
;     ...
;         const bool has_next = S.next(ui + 1, nxt);
.LBB0_183:
	s_add_i32 s72, s72, 1
	s_mul_i32 s0, s72, s77
	s_mul_hi_u32 s1, s72, s78
	s_add_i32 s1, s1, s0
	s_mul_i32 s0, s72, s78
	s_add_u32 s42, s0, s2
	s_addc_u32 s43, s1, s79
	v_cmp_gt_i64_e32 vcc, s[42:43], v[144:145]
	v_cmp_lt_i64_e64 s[0:1], s[42:43], v[142:143]
	s_cbranch_vccnz .LBB0_185
	s_and_b32 s5, s42, 7
	s_lshr_b32 s15, s42, 3
	s_cmpk_lt_u32 s15, 0x18c
	s_cbranch_scc0 .Lxpl2_xp
	s_mul_i32 s5, s5, 0x18c
	s_add_i32 s5, s5, s15
	s_lshr_b32 s16, s5, 6
	s_mul_i32 s16, s16, 0xaaab
	s_lshr_b32 s16, s16, 17
	s_mul_i32 s17, s16, 0xc0
	s_sub_i32 s33, s5, s17
	s_mov_b32 s14, 4
	s_branch .Lxpl2_common
.Lxpl2_xp:
	s_mul_i32 s5, s5, 66
	s_add_i32 s5, s5, s15
	s_sub_i32 s5, s5, 0x18c
	s_lshr_b32 s16, s5, 5
	s_and_b32 s33, s5, 31
	s_mov_b32 s14, 0
.Lxpl2_common:
	s_lshl_b32 s16, s16, 3
	s_cmp_eq_u32 s16, 0x80
	s_cselect_b32 s17, 3, 7
	s_cselect_b32 s35, 2, 3
	s_and_b32 s40, s33, s17
	s_add_i32 s40, s40, s16
	s_lshr_b32 s33, s33, s35
	s_add_i32 s14, s14, s33
